# attention: running max advanced only when the tile max exceeds it by >4 (log2), accumulator rescale skipped when alpha==1 for the whole wave; same softmax function
# speedup vs baseline: 1.0021x; 1.0021x over previous
.LBB0_323:
	s_nop 10
	v_max3_f32 v0, v80, s18, v81
	v_max3_f32 v0, v0, v82, v83
	v_max3_f32 v0, v0, v84, v85
	v_max3_f32 v0, v0, v86, v87
	v_max3_f32 v0, v0, v88, v89
	v_max3_f32 v0, v0, v90, v91
	v_max3_f32 v0, v0, v92, v93
	v_max3_f32 v0, v0, v94, v95
	ds_bpermute_b32 v2, v209, v0
	s_and_b64 vcc, exec, s[38:39]
	s_waitcnt lgkmcnt(0)
	v_max3_f32 v234, v231, v0, v2
	v_sub_f32_e32 v255, v234, v231
	v_cmp_lt_f32_e64 s[98:99], 4.0, v255
	s_nop 1
	v_cndmask_b32_e64 v234, v231, v234, s[98:99]
	v_sub_f32_e32 v2, v81, v234
	v_exp_f32_e32 v14, v2
	v_sub_f32_e32 v2, v82, v234
	v_exp_f32_e32 v232, v2
	v_sub_f32_e32 v2, v83, v234
	v_exp_f32_e32 v236, v2
	v_sub_f32_e32 v2, v84, v234
	v_exp_f32_e32 v237, v2
	v_sub_f32_e32 v2, v85, v234
	v_exp_f32_e32 v238, v2
	v_sub_f32_e32 v2, v86, v234
	v_exp_f32_e32 v239, v2
	v_sub_f32_e32 v2, v87, v234
	v_exp_f32_e32 v240, v2
	v_sub_f32_e32 v2, v88, v234
	v_exp_f32_e32 v241, v2
	v_sub_f32_e32 v2, v89, v234
	v_exp_f32_e32 v242, v2
	v_sub_f32_e32 v2, v90, v234
	v_exp_f32_e32 v243, v2
	v_sub_f32_e32 v2, v91, v234
	v_exp_f32_e32 v244, v2
	v_sub_f32_e32 v2, v92, v234
	v_exp_f32_e32 v245, v2
	v_sub_f32_e32 v2, v93, v234
	v_exp_f32_e32 v246, v2
	v_sub_f32_e32 v2, v94, v234
	v_sub_f32_e32 v0, v80, v234
	v_exp_f32_e32 v247, v2
	v_sub_f32_e32 v2, v95, v234
	v_mfma_f32_32x32x16_bf16 v[80:95], v[168:171], v[112:115], 0
	v_exp_f32_e32 v0, v0
	v_exp_f32_e32 v248, v2
	v_cvt_pk_bf16_f32 v6, v0, v14
	v_cvt_pk_bf16_f32 v7, v232, v236
	v_cvt_pk_bf16_f32 v8, v237, v238
	v_cvt_pk_bf16_f32 v9, v239, v240
	v_cvt_pk_bf16_f32 v2, v241, v242
	v_mfma_f32_32x32x16_bf16 v[80:95], v[164:167], v[116:119], v[80:95]
	v_cvt_pk_bf16_f32 v3, v243, v244
	v_cvt_pk_bf16_f32 v4, v245, v246
	v_cvt_pk_bf16_f32 v5, v247, v248
	v_mfma_f32_32x32x16_bf16 v[80:95], v[10:13], v[120:123], v[80:95]
	v_mfma_f32_32x32x16_bf16 v[80:95], v[160:163], v[124:127], v[80:95]
	s_cbranch_vccnz .LBB0_326
	s_cmp_lt_i32 s3, s62
	s_cselect_b64 s[0:1], -1, 0
	s_cmp_gt_i32 s3, s55
	s_cselect_b64 s[26:27], -1, 0
	s_or_b64 s[0:1], s[0:1], s[26:27]
	s_andn2_b64 vcc, exec, s[0:1]
	s_cbranch_vccnz .LBB0_326
	s_sub_i32 s0, s33, s63
	v_add_u32_e32 v10, s0, v214
	v_cmp_lt_u32_e32 vcc, s66, v10
	v_add_u32_e32 v10, s0, v215
	s_nop 0
	v_cndmask_b32_e32 v80, v200, v80, vcc
	v_cmp_lt_u32_e32 vcc, s66, v10
	v_add_u32_e32 v10, s0, v216
	s_nop 0
	v_cndmask_b32_e32 v81, v200, v81, vcc
	v_cmp_lt_u32_e32 vcc, s66, v10
	v_add_u32_e32 v10, s0, v217
	s_nop 0
	v_cndmask_b32_e32 v82, v200, v82, vcc
	v_cmp_lt_u32_e32 vcc, s66, v10
	v_add_u32_e32 v10, s0, v218
	s_nop 0
	v_cndmask_b32_e32 v83, v200, v83, vcc
	v_cmp_lt_u32_e32 vcc, s66, v10
	v_add_u32_e32 v10, s0, v219
	s_nop 0
	v_cndmask_b32_e32 v84, v200, v84, vcc
	v_cmp_lt_u32_e32 vcc, s66, v10
	v_add_u32_e32 v10, s0, v220
	s_nop 0
	v_cndmask_b32_e32 v85, v200, v85, vcc
	v_cmp_lt_u32_e32 vcc, s66, v10
	v_add_u32_e32 v10, s0, v221
	s_nop 0
	v_cndmask_b32_e32 v86, v200, v86, vcc
	v_cmp_lt_u32_e32 vcc, s66, v10
	v_add_u32_e32 v10, s0, v222
	s_nop 0
	v_cndmask_b32_e32 v87, v200, v87, vcc
	v_cmp_lt_u32_e32 vcc, s66, v10
	v_add_u32_e32 v10, s0, v223
	s_nop 0
	v_cndmask_b32_e32 v88, v200, v88, vcc
	v_cmp_lt_u32_e32 vcc, s66, v10
	v_add_u32_e32 v10, s0, v224
	s_nop 0
	v_cndmask_b32_e32 v89, v200, v89, vcc
	v_cmp_lt_u32_e32 vcc, s66, v10
	v_add_u32_e32 v10, s0, v225
	s_nop 0
	v_cndmask_b32_e32 v90, v200, v90, vcc
	v_cmp_lt_u32_e32 vcc, s66, v10
	v_add_u32_e32 v10, s0, v226
	s_nop 0
	v_cndmask_b32_e32 v91, v200, v91, vcc
	v_cmp_lt_u32_e32 vcc, s66, v10
	v_add_u32_e32 v10, s0, v227
	s_nop 0
	v_cndmask_b32_e32 v92, v200, v92, vcc
	v_cmp_lt_u32_e32 vcc, s66, v10
	v_add_u32_e32 v10, s0, v228
	s_nop 0
	v_cndmask_b32_e32 v93, v200, v93, vcc
	v_cmp_lt_u32_e32 vcc, s66, v10
	v_add_u32_e32 v10, s0, v229
	s_nop 0
	v_cndmask_b32_e32 v94, v200, v94, vcc
	v_cmp_lt_u32_e32 vcc, s66, v10
	s_nop 1
	v_cndmask_b32_e32 v95, v200, v95, vcc
.LBB0_326:
	v_add_f32_e32 v0, 0, v0
	v_add_f32_e32 v0, v14, v0
	v_add_f32_e32 v0, v232, v0
	v_add_f32_e32 v0, v236, v0
	v_add_f32_e32 v0, v237, v0
	v_add_f32_e32 v0, v238, v0
	v_add_f32_e32 v0, v239, v0
	v_add_f32_e32 v0, v240, v0
	v_add_f32_e32 v0, v241, v0
	v_add_f32_e32 v0, v242, v0
	v_add_f32_e32 v0, v243, v0
	v_add_f32_e32 v0, v244, v0
	v_add_f32_e32 v0, v245, v0
	v_add_f32_e32 v0, v246, v0
	v_sub_f32_e32 v10, v231, v234
	v_add_f32_e32 v0, v247, v0
	v_add_f32_e32 v232, v248, v0
	v_exp_f32_e32 v0, v10
	v_add_u32_e32 v231, 0x1000, v230
	s_add_i32 s0, s64, -7
	s_cmp_ge_i32 s0, s56
	v_fmac_f32_e32 v232, v233, v0
	s_mov_b64 vcc, s[98:99]
	s_cbranch_vccz .Lrs_0
	v_mul_f32_e32 v78, v0, v78
	v_mul_f32_e32 v79, v0, v79
	v_mul_f32_e32 v76, v0, v76
	v_mul_f32_e32 v77, v0, v77
	v_mul_f32_e32 v74, v0, v74
	v_mul_f32_e32 v75, v0, v75
	v_mul_f32_e32 v72, v0, v72
	v_mul_f32_e32 v73, v0, v73
	v_mul_f32_e32 v70, v0, v70
	v_mul_f32_e32 v71, v0, v71
	v_mul_f32_e32 v68, v0, v68
	v_mul_f32_e32 v69, v0, v69
	v_mul_f32_e32 v66, v0, v66
	v_mul_f32_e32 v67, v0, v67
	v_mul_f32_e32 v64, v0, v64
	v_mul_f32_e32 v65, v0, v65
	v_mul_f32_e32 v62, v0, v62
	v_mul_f32_e32 v63, v0, v63
	v_mul_f32_e32 v60, v0, v60
	v_mul_f32_e32 v61, v0, v61
	v_mul_f32_e32 v58, v0, v58
	v_mul_f32_e32 v59, v0, v59
	v_mul_f32_e32 v56, v0, v56
	v_mul_f32_e32 v57, v0, v57
	v_mul_f32_e32 v54, v0, v54
	v_mul_f32_e32 v55, v0, v55
	v_mul_f32_e32 v52, v0, v52
	v_mul_f32_e32 v53, v0, v53
	v_mul_f32_e32 v50, v0, v50
	v_mul_f32_e32 v51, v0, v51
	v_mul_f32_e32 v48, v0, v48
	v_mul_f32_e32 v49, v0, v49
.Lrs_0:
	v_max3_f32 v0, v80, s18, v81
	v_max3_f32 v0, v0, v82, v83
	v_max3_f32 v0, v0, v84, v85
	v_max3_f32 v0, v0, v86, v87
	v_max3_f32 v0, v0, v88, v89
	v_max3_f32 v0, v0, v90, v91
	v_max3_f32 v0, v0, v92, v93
	v_max3_f32 v0, v0, v94, v95
	ds_bpermute_b32 v10, v209, v0
	s_waitcnt lgkmcnt(0)
	v_max3_f32 v14, v235, v0, v10
	v_sub_f32_e32 v255, v14, v235
	v_cmp_lt_f32_e64 s[98:99], 4.0, v255
	s_nop 1
	v_cndmask_b32_e64 v14, v235, v14, s[98:99]
	v_sub_f32_e32 v0, v80, v14
	v_exp_f32_e32 v11, v0
	v_sub_f32_e32 v12, v81, v14
	v_exp_f32_e32 v12, v12
	v_sub_f32_e32 v13, v82, v14
	v_exp_f32_e32 v13, v13
	v_sub_f32_e32 v80, v83, v14
	v_exp_f32_e32 v81, v80
	v_sub_f32_e32 v80, v84, v14
	v_add_f32_e32 v0, 0, v11
	v_exp_f32_e32 v82, v80
	v_sub_f32_e32 v80, v85, v14
	v_add_f32_e32 v0, v12, v0
	v_exp_f32_e32 v83, v80
	v_sub_f32_e32 v80, v86, v14
	v_add_f32_e32 v0, v13, v0
	v_exp_f32_e32 v84, v80
	v_sub_f32_e32 v80, v87, v14
	v_add_f32_e32 v0, v81, v0
	v_exp_f32_e32 v85, v80
	v_sub_f32_e32 v80, v88, v14
	v_add_f32_e32 v0, v82, v0
	v_exp_f32_e32 v86, v80
	v_sub_f32_e32 v80, v89, v14
	v_add_f32_e32 v0, v83, v0
	v_exp_f32_e32 v87, v80
	v_sub_f32_e32 v80, v90, v14
	v_add_f32_e32 v0, v84, v0
	v_exp_f32_e32 v88, v80
	v_sub_f32_e32 v80, v91, v14
	v_add_f32_e32 v0, v85, v0
	v_exp_f32_e32 v89, v80
	v_sub_f32_e32 v80, v92, v14
	v_add_f32_e32 v0, v86, v0
	v_exp_f32_e32 v90, v80
	v_sub_f32_e32 v80, v93, v14
	v_add_f32_e32 v0, v87, v0
	v_exp_f32_e32 v91, v80
	v_sub_f32_e32 v80, v94, v14
	v_add_f32_e32 v0, v88, v0
	v_exp_f32_e32 v92, v80
	v_sub_f32_e32 v80, v95, v14
	v_sub_f32_e32 v10, v235, v14
	v_add_f32_e32 v0, v89, v0
	v_exp_f32_e32 v93, v80
	v_add_f32_e32 v0, v90, v0
	v_exp_f32_e32 v10, v10
	v_add_f32_e32 v0, v91, v0
	v_add_f32_e32 v0, v92, v0
	v_add_f32_e32 v0, v93, v0
	v_fmac_f32_e32 v0, v15, v10
	s_mov_b64 vcc, s[98:99]
	s_cbranch_vccz .Lrs_1
	v_mul_f32_e32 v46, v10, v46
	v_mul_f32_e32 v47, v10, v47
	v_mul_f32_e32 v44, v10, v44
	v_mul_f32_e32 v45, v10, v45
	v_mul_f32_e32 v42, v10, v42
	v_mul_f32_e32 v43, v10, v43
	v_mul_f32_e32 v40, v10, v40
	v_mul_f32_e32 v41, v10, v41
	v_mul_f32_e32 v38, v10, v38
	v_mul_f32_e32 v39, v10, v39
	v_mul_f32_e32 v36, v10, v36
	v_mul_f32_e32 v37, v10, v37
	v_mul_f32_e32 v34, v10, v34
	v_mul_f32_e32 v35, v10, v35
	v_mul_f32_e32 v32, v10, v32
	v_mul_f32_e32 v33, v10, v33
	v_mul_f32_e32 v30, v10, v30
	v_mul_f32_e32 v31, v10, v31
	v_mul_f32_e32 v28, v10, v28
	v_mul_f32_e32 v29, v10, v29
	v_mul_f32_e32 v26, v10, v26
	v_mul_f32_e32 v27, v10, v27
	v_mul_f32_e32 v24, v10, v24
	v_mul_f32_e32 v25, v10, v25
	v_mul_f32_e32 v22, v10, v22
	v_mul_f32_e32 v23, v10, v23
	v_mul_f32_e32 v20, v10, v20
	v_mul_f32_e32 v21, v10, v21
	v_mul_f32_e32 v18, v10, v18
	v_mul_f32_e32 v19, v10, v19
	v_mul_f32_e32 v16, v10, v16
	v_mul_f32_e32 v17, v10, v17
.Lrs_1:
	v_cvt_pk_bf16_f32 v80, v11, v12
	v_cvt_pk_bf16_f32 v82, v82, v83
	v_cvt_pk_bf16_f32 v83, v84, v85
	v_cvt_pk_bf16_f32 v10, v86, v87
	v_cvt_pk_bf16_f32 v11, v88, v89
	v_cvt_pk_bf16_f32 v12, v90, v91
	ds_read2_b64 v[84:87], v231 offset0:64 offset1:66
	ds_read2_b64 v[88:91], v231 offset0:68 offset1:70
	v_add_u32_e32 v15, 0x1800, v230
	v_cvt_pk_bf16_f32 v81, v13, v81
	s_waitcnt lgkmcnt(1)
	v_mfma_f32_32x32x16_bf16 v[64:79], v[84:87], v[6:9], v[64:79]
	v_cvt_pk_bf16_f32 v13, v92, v93
	v_mfma_f32_32x32x16_bf16 v[32:47], v[84:87], v[80:83], v[32:47]
	ds_read2_b64 v[84:87], v15 offset0:128 offset1:130
	s_waitcnt lgkmcnt(0)
	v_mfma_f32_32x32x16_bf16 v[48:63], v[84:87], v[6:9], v[48:63]
	ds_read2_b64 v[6:9], v15 offset0:132 offset1:134
	s_waitcnt lgkmcnt(0)
	s_barrier
	v_mfma_f32_32x32x16_bf16 v[16:31], v[84:87], v[80:83], v[16:31]
	v_mfma_f32_32x32x16_bf16 v[64:79], v[88:91], v[2:5], v[64:79]
	v_mfma_f32_32x32x16_bf16 v[32:47], v[88:91], v[10:13], v[32:47]
	v_mfma_f32_32x32x16_bf16 v[48:63], v[6:9], v[2:5], v[48:63]
	v_mfma_f32_32x32x16_bf16 v[16:31], v[6:9], v[10:13], v[16:31]
	s_cbranch_scc1 .LBB0_330
	s_cmp_lt_i32 s0, s53
	s_cselect_b64 s[34:35], -1, 0
	s_mov_b64 s[40:41], -1
	s_and_b64 vcc, exec, s[34:35]
	s_cbranch_vccz .LBB0_333
	s_andn2_b64 vcc, exec, s[40:41]
	s_cbranch_vccz .LBB0_334

.LBB0_344:
	s_nop 10
	v_max3_f32 v2, v80, s18, v81
	v_max3_f32 v2, v2, v82, v83
	v_max3_f32 v2, v2, v84, v85
	v_max3_f32 v2, v2, v86, v87
	v_max3_f32 v2, v2, v88, v89
	v_max3_f32 v2, v2, v90, v91
	v_max3_f32 v2, v2, v92, v93
	v_max3_f32 v2, v2, v94, v95
	ds_bpermute_b32 v3, v209, v2
	s_and_b64 vcc, exec, s[40:41]
	s_waitcnt lgkmcnt(0)
	v_max3_f32 v233, v234, v2, v3
	v_sub_f32_e32 v255, v233, v234
	v_cmp_lt_f32_e64 s[98:99], 4.0, v255
	s_nop 1
	v_cndmask_b32_e64 v233, v234, v233, s[98:99]
	v_sub_f32_e32 v2, v80, v233
	v_exp_f32_e32 v235, v2
	v_sub_f32_e32 v2, v81, v233
	v_exp_f32_e32 v236, v2
	v_sub_f32_e32 v2, v82, v233
	v_exp_f32_e32 v237, v2
	v_sub_f32_e32 v2, v83, v233
	v_exp_f32_e32 v238, v2
	v_sub_f32_e32 v2, v84, v233
	v_exp_f32_e32 v239, v2
	v_sub_f32_e32 v2, v85, v233
	v_exp_f32_e32 v240, v2
	v_sub_f32_e32 v2, v86, v233
	v_exp_f32_e32 v241, v2
	v_sub_f32_e32 v2, v87, v233
	v_exp_f32_e32 v242, v2
	v_sub_f32_e32 v2, v88, v233
	v_exp_f32_e32 v243, v2
	v_sub_f32_e32 v2, v89, v233
	v_exp_f32_e32 v244, v2
	v_sub_f32_e32 v2, v90, v233
	v_exp_f32_e32 v245, v2
	v_sub_f32_e32 v2, v91, v233
	v_exp_f32_e32 v246, v2
	v_sub_f32_e32 v2, v92, v233
	v_exp_f32_e32 v247, v2
	v_sub_f32_e32 v2, v93, v233
	v_exp_f32_e32 v248, v2
	v_sub_f32_e32 v2, v94, v233
	v_exp_f32_e32 v249, v2
	v_sub_f32_e32 v2, v95, v233
	v_mfma_f32_32x32x16_bf16 v[80:95], v[168:171], v[112:115], 0
	v_exp_f32_e32 v250, v2
	v_cvt_pk_bf16_f32 v6, v235, v236
	v_cvt_pk_bf16_f32 v7, v237, v238
	v_cvt_pk_bf16_f32 v8, v239, v240
	v_cvt_pk_bf16_f32 v9, v241, v242
	v_cvt_pk_bf16_f32 v2, v243, v244
	v_cvt_pk_bf16_f32 v3, v245, v246
	v_mfma_f32_32x32x16_bf16 v[80:95], v[164:167], v[116:119], v[80:95]
	v_cvt_pk_bf16_f32 v4, v247, v248
	v_cvt_pk_bf16_f32 v5, v249, v250
	v_mfma_f32_32x32x16_bf16 v[80:95], v[10:13], v[120:123], v[80:95]
	v_mfma_f32_32x32x16_bf16 v[80:95], v[160:163], v[124:127], v[80:95]
	s_cbranch_vccnz .LBB0_347
	s_cmp_lt_i32 s3, s62
	s_cselect_b64 s[0:1], -1, 0
	s_cmp_gt_i32 s3, s55
	s_cselect_b64 s[26:27], -1, 0
	s_or_b64 s[0:1], s[0:1], s[26:27]
	s_andn2_b64 vcc, exec, s[0:1]
	s_cbranch_vccnz .LBB0_347
	s_sub_i32 s0, s33, s63
	v_add_u32_e32 v10, s0, v214
	v_cmp_lt_u32_e32 vcc, s66, v10
	v_add_u32_e32 v10, s0, v215
	s_nop 0
	v_cndmask_b32_e32 v80, v200, v80, vcc
	v_cmp_lt_u32_e32 vcc, s66, v10
	v_add_u32_e32 v10, s0, v216
	s_nop 0
	v_cndmask_b32_e32 v81, v200, v81, vcc
	v_cmp_lt_u32_e32 vcc, s66, v10
	v_add_u32_e32 v10, s0, v217
	s_nop 0
	v_cndmask_b32_e32 v82, v200, v82, vcc
	v_cmp_lt_u32_e32 vcc, s66, v10
	v_add_u32_e32 v10, s0, v218
	s_nop 0
	v_cndmask_b32_e32 v83, v200, v83, vcc
	v_cmp_lt_u32_e32 vcc, s66, v10
	v_add_u32_e32 v10, s0, v219
	s_nop 0
	v_cndmask_b32_e32 v84, v200, v84, vcc
	v_cmp_lt_u32_e32 vcc, s66, v10
	v_add_u32_e32 v10, s0, v220
	s_nop 0
	v_cndmask_b32_e32 v85, v200, v85, vcc
	v_cmp_lt_u32_e32 vcc, s66, v10
	v_add_u32_e32 v10, s0, v221
	s_nop 0
	v_cndmask_b32_e32 v86, v200, v86, vcc
	v_cmp_lt_u32_e32 vcc, s66, v10
	v_add_u32_e32 v10, s0, v222
	s_nop 0
	v_cndmask_b32_e32 v87, v200, v87, vcc
	v_cmp_lt_u32_e32 vcc, s66, v10
	v_add_u32_e32 v10, s0, v223
	s_nop 0
	v_cndmask_b32_e32 v88, v200, v88, vcc
	v_cmp_lt_u32_e32 vcc, s66, v10
	v_add_u32_e32 v10, s0, v224
	s_nop 0
	v_cndmask_b32_e32 v89, v200, v89, vcc
	v_cmp_lt_u32_e32 vcc, s66, v10
	v_add_u32_e32 v10, s0, v225
	s_nop 0
	v_cndmask_b32_e32 v90, v200, v90, vcc
	v_cmp_lt_u32_e32 vcc, s66, v10
	v_add_u32_e32 v10, s0, v226
	s_nop 0
	v_cndmask_b32_e32 v91, v200, v91, vcc
	v_cmp_lt_u32_e32 vcc, s66, v10
	v_add_u32_e32 v10, s0, v227
	s_nop 0
	v_cndmask_b32_e32 v92, v200, v92, vcc
	v_cmp_lt_u32_e32 vcc, s66, v10
	v_add_u32_e32 v10, s0, v228
	s_nop 0
	v_cndmask_b32_e32 v93, v200, v93, vcc
	v_cmp_lt_u32_e32 vcc, s66, v10
	v_add_u32_e32 v10, s0, v229
	s_nop 0
	v_cndmask_b32_e32 v94, v200, v94, vcc
	v_cmp_lt_u32_e32 vcc, s66, v10
	s_nop 1
	v_cndmask_b32_e32 v95, v200, v95, vcc
.LBB0_347:
	v_add_f32_e32 v11, 0, v235
	v_add_f32_e32 v11, v236, v11
	v_add_f32_e32 v11, v237, v11
	v_add_f32_e32 v11, v238, v11
	v_add_f32_e32 v11, v239, v11
	v_add_f32_e32 v11, v240, v11
	v_add_f32_e32 v11, v241, v11
	v_add_f32_e32 v11, v242, v11
	v_add_f32_e32 v11, v243, v11
	v_add_f32_e32 v11, v244, v11
	v_add_f32_e32 v11, v245, v11
	v_sub_f32_e32 v10, v234, v233
	v_add_f32_e32 v11, v246, v11
	v_add_f32_e32 v11, v247, v11
	v_exp_f32_e32 v10, v10
	v_add_f32_e32 v11, v248, v11
	v_add_f32_e32 v11, v249, v11
	v_add_f32_e32 v160, v250, v11
	v_fmac_f32_e32 v160, v232, v10
	s_mov_b64 vcc, s[98:99]
	s_cbranch_vccz .Lrs_2
	v_mul_f32_e32 v78, v10, v78
	v_mul_f32_e32 v79, v10, v79
	v_mul_f32_e32 v76, v10, v76
	v_mul_f32_e32 v77, v10, v77
	v_mul_f32_e32 v74, v10, v74
	v_mul_f32_e32 v75, v10, v75
	v_mul_f32_e32 v72, v10, v72
	v_mul_f32_e32 v73, v10, v73
	v_mul_f32_e32 v70, v10, v70
	v_mul_f32_e32 v71, v10, v71
	v_mul_f32_e32 v68, v10, v68
	v_mul_f32_e32 v69, v10, v69
	v_mul_f32_e32 v66, v10, v66
	v_mul_f32_e32 v67, v10, v67
	v_mul_f32_e32 v64, v10, v64
	v_mul_f32_e32 v65, v10, v65
	v_mul_f32_e32 v62, v10, v62
	v_mul_f32_e32 v63, v10, v63
	v_mul_f32_e32 v60, v10, v60
	v_mul_f32_e32 v61, v10, v61
	v_mul_f32_e32 v58, v10, v58
	v_mul_f32_e32 v59, v10, v59
	v_mul_f32_e32 v56, v10, v56
	v_mul_f32_e32 v57, v10, v57
	v_mul_f32_e32 v54, v10, v54
	v_mul_f32_e32 v55, v10, v55
	v_mul_f32_e32 v52, v10, v52
	v_mul_f32_e32 v53, v10, v53
	v_mul_f32_e32 v50, v10, v50
	v_mul_f32_e32 v51, v10, v51
	v_mul_f32_e32 v48, v10, v48
	v_mul_f32_e32 v49, v10, v49
.Lrs_2:
	v_max3_f32 v10, v80, s18, v81
	v_max3_f32 v10, v10, v82, v83
	v_max3_f32 v10, v10, v84, v85
	v_max3_f32 v10, v10, v86, v87
	v_max3_f32 v10, v10, v88, v89
	v_max3_f32 v10, v10, v90, v91
	v_max3_f32 v10, v10, v92, v93
	v_max3_f32 v10, v10, v94, v95
	ds_bpermute_b32 v11, v209, v10
	v_mov_b32_e32 v232, v160
	s_waitcnt lgkmcnt(0)
	v_max3_f32 v161, v14, v10, v11
	v_sub_f32_e32 v255, v161, v14
	v_cmp_lt_f32_e64 s[98:99], 4.0, v255
	s_nop 1
	v_cndmask_b32_e64 v161, v14, v161, s[98:99]
	v_sub_f32_e32 v11, v80, v161
	v_exp_f32_e32 v11, v11
	v_sub_f32_e32 v13, v81, v161
	v_sub_f32_e32 v10, v14, v161
	v_exp_f32_e32 v13, v13
	v_sub_f32_e32 v14, v82, v161
	v_exp_f32_e32 v14, v14
	v_sub_f32_e32 v80, v83, v161
	v_exp_f32_e32 v81, v80
	v_sub_f32_e32 v80, v84, v161
	v_add_f32_e32 v12, 0, v11
	v_exp_f32_e32 v82, v80
	v_sub_f32_e32 v80, v85, v161
	v_add_f32_e32 v12, v13, v12
	v_exp_f32_e32 v83, v80
	v_sub_f32_e32 v80, v86, v161
	v_add_f32_e32 v12, v14, v12
	v_exp_f32_e32 v85, v80
	v_sub_f32_e32 v80, v87, v161
	v_add_f32_e32 v12, v81, v12
	v_exp_f32_e32 v86, v80
	v_sub_f32_e32 v80, v88, v161
	v_add_f32_e32 v12, v82, v12
	v_exp_f32_e32 v87, v80
	v_sub_f32_e32 v80, v89, v161
	v_add_f32_e32 v12, v83, v12
	v_exp_f32_e32 v88, v80
	v_sub_f32_e32 v80, v90, v161
	v_add_f32_e32 v12, v85, v12
	v_exp_f32_e32 v89, v80
	v_sub_f32_e32 v80, v91, v161
	v_add_f32_e32 v12, v86, v12
	v_exp_f32_e32 v90, v80
	v_sub_f32_e32 v80, v92, v161
	v_add_f32_e32 v12, v87, v12
	v_exp_f32_e32 v91, v80
	v_sub_f32_e32 v80, v93, v161
	v_add_f32_e32 v12, v88, v12
	v_exp_f32_e32 v92, v80
	v_sub_f32_e32 v80, v94, v161
	v_add_f32_e32 v12, v89, v12
	v_exp_f32_e32 v93, v80
	v_sub_f32_e32 v80, v95, v161
	v_add_f32_e32 v12, v90, v12
	v_exp_f32_e32 v94, v80
	v_add_f32_e32 v12, v91, v12
	v_exp_f32_e32 v10, v10
	v_add_f32_e32 v12, v92, v12
	v_add_f32_e32 v12, v93, v12
	v_add_f32_e32 v84, v94, v12
	v_fmac_f32_e32 v84, v0, v10
	v_add_u32_e32 v0, 0x3800, v230
	s_mov_b64 vcc, s[98:99]
	s_cbranch_vccz .Lrs_3
	v_mul_f32_e32 v46, v10, v46
	v_mul_f32_e32 v47, v10, v47
	v_mul_f32_e32 v44, v10, v44
	v_mul_f32_e32 v45, v10, v45
	v_mul_f32_e32 v42, v10, v42
	v_mul_f32_e32 v43, v10, v43
	v_mul_f32_e32 v40, v10, v40
	v_mul_f32_e32 v41, v10, v41
	v_mul_f32_e32 v38, v10, v38
	v_mul_f32_e32 v39, v10, v39
	v_mul_f32_e32 v36, v10, v36
	v_mul_f32_e32 v37, v10, v37
	v_mul_f32_e32 v34, v10, v34
	v_mul_f32_e32 v35, v10, v35
	v_mul_f32_e32 v32, v10, v32
	v_mul_f32_e32 v33, v10, v33
	v_mul_f32_e32 v30, v10, v30
	v_mul_f32_e32 v31, v10, v31
	v_mul_f32_e32 v28, v10, v28
	v_mul_f32_e32 v29, v10, v29
	v_mul_f32_e32 v26, v10, v26
	v_mul_f32_e32 v27, v10, v27
	v_mul_f32_e32 v24, v10, v24
	v_mul_f32_e32 v25, v10, v25
	v_mul_f32_e32 v22, v10, v22
	v_mul_f32_e32 v23, v10, v23
	v_mul_f32_e32 v20, v10, v20
	v_mul_f32_e32 v21, v10, v21
	v_mul_f32_e32 v18, v10, v18
	v_mul_f32_e32 v19, v10, v19
	v_mul_f32_e32 v16, v10, v16
	v_mul_f32_e32 v17, v10, v17
.Lrs_3:
	v_cvt_pk_bf16_f32 v80, v11, v13
	v_cvt_pk_bf16_f32 v82, v82, v83
	v_cvt_pk_bf16_f32 v83, v85, v86
	v_cvt_pk_bf16_f32 v10, v87, v88
	v_cvt_pk_bf16_f32 v11, v89, v90
	v_cvt_pk_bf16_f32 v12, v91, v92
	v_cvt_pk_bf16_f32 v13, v93, v94
	ds_read2_b64 v[86:89], v0 offset1:2
	ds_read2_b64 v[90:93], v0 offset0:4 offset1:6
	v_add_u32_e32 v0, 0x4000, v230
	v_cvt_pk_bf16_f32 v81, v14, v81
	s_waitcnt lgkmcnt(1)
	v_mfma_f32_32x32x16_bf16 v[64:79], v[86:89], v[6:9], v[64:79]
	v_mov_b32_e32 v14, v161
	v_mfma_f32_32x32x16_bf16 v[32:47], v[86:89], v[80:83], v[32:47]
	ds_read2_b64 v[86:89], v0 offset0:64 offset1:66
	s_waitcnt lgkmcnt(0)
	v_mfma_f32_32x32x16_bf16 v[48:63], v[86:89], v[6:9], v[48:63]
	ds_read2_b64 v[6:9], v0 offset0:68 offset1:70
	v_mov_b32_e32 v0, v84
	s_waitcnt lgkmcnt(0)
	s_barrier
	v_mfma_f32_32x32x16_bf16 v[16:31], v[86:89], v[80:83], v[16:31]
	v_mfma_f32_32x32x16_bf16 v[64:79], v[90:93], v[2:5], v[64:79]
	v_mfma_f32_32x32x16_bf16 v[32:47], v[90:93], v[10:13], v[32:47]
	v_mfma_f32_32x32x16_bf16 v[48:63], v[6:9], v[2:5], v[48:63]
	v_mfma_f32_32x32x16_bf16 v[16:31], v[6:9], v[10:13], v[16:31]
	s_add_i32 s0, s64, -6
	s_cmp_ge_i32 s0, s56
	s_cbranch_scc1 .LBB0_331

.LBB0_362:
	s_nop 10
	v_max3_f32 v2, v80, s18, v81
	v_max3_f32 v2, v2, v82, v83
	v_max3_f32 v2, v2, v84, v85
	v_max3_f32 v2, v2, v86, v87
	v_max3_f32 v2, v2, v88, v89
	v_max3_f32 v2, v2, v90, v91
	v_max3_f32 v2, v2, v92, v93
	v_max3_f32 v2, v2, v94, v95
	ds_bpermute_b32 v3, v209, v2
	s_and_b64 vcc, exec, s[40:41]
	s_waitcnt lgkmcnt(0)
	v_max3_f32 v234, v233, v2, v3
	v_sub_f32_e32 v255, v234, v233
	v_cmp_lt_f32_e64 s[98:99], 4.0, v255
	s_nop 1
	v_cndmask_b32_e64 v234, v233, v234, s[98:99]
	v_sub_f32_e32 v2, v80, v234
	v_exp_f32_e32 v235, v2
	v_sub_f32_e32 v2, v81, v234
	v_exp_f32_e32 v236, v2
	v_sub_f32_e32 v2, v82, v234
	v_exp_f32_e32 v237, v2
	v_sub_f32_e32 v2, v83, v234
	v_exp_f32_e32 v238, v2
	v_sub_f32_e32 v2, v84, v234
	v_exp_f32_e32 v239, v2
	v_sub_f32_e32 v2, v85, v234
	v_exp_f32_e32 v240, v2
	v_sub_f32_e32 v2, v86, v234
	v_exp_f32_e32 v241, v2
	v_sub_f32_e32 v2, v87, v234
	v_exp_f32_e32 v242, v2
	v_sub_f32_e32 v2, v88, v234
	v_exp_f32_e32 v243, v2
	v_sub_f32_e32 v2, v89, v234
	v_exp_f32_e32 v244, v2
	v_sub_f32_e32 v2, v90, v234
	v_exp_f32_e32 v245, v2
	v_sub_f32_e32 v2, v91, v234
	v_exp_f32_e32 v246, v2
	v_sub_f32_e32 v2, v92, v234
	v_exp_f32_e32 v247, v2
	v_sub_f32_e32 v2, v93, v234
	v_exp_f32_e32 v248, v2
	v_sub_f32_e32 v2, v94, v234
	v_exp_f32_e32 v249, v2
	v_sub_f32_e32 v2, v95, v234
	v_mfma_f32_32x32x16_bf16 v[80:95], v[168:171], v[112:115], 0
	v_exp_f32_e32 v250, v2
	v_cvt_pk_bf16_f32 v6, v235, v236
	v_cvt_pk_bf16_f32 v7, v237, v238
	v_cvt_pk_bf16_f32 v8, v239, v240
	v_cvt_pk_bf16_f32 v9, v241, v242
	v_cvt_pk_bf16_f32 v2, v243, v244
	v_cvt_pk_bf16_f32 v3, v245, v246
	v_mfma_f32_32x32x16_bf16 v[80:95], v[164:167], v[116:119], v[80:95]
	v_cvt_pk_bf16_f32 v4, v247, v248
	v_cvt_pk_bf16_f32 v5, v249, v250
	v_mfma_f32_32x32x16_bf16 v[80:95], v[10:13], v[120:123], v[80:95]
	v_mfma_f32_32x32x16_bf16 v[80:95], v[160:163], v[124:127], v[80:95]
	s_cbranch_vccnz .LBB0_365
	s_cmp_lt_i32 s3, s62
	s_cselect_b64 s[0:1], -1, 0
	s_cmp_gt_i32 s3, s55
	s_cselect_b64 s[26:27], -1, 0
	s_or_b64 s[0:1], s[0:1], s[26:27]
	s_andn2_b64 vcc, exec, s[0:1]
	s_cbranch_vccnz .LBB0_365
	s_sub_i32 s0, s33, s63
	v_add_u32_e32 v10, s0, v214
	v_cmp_lt_u32_e32 vcc, s66, v10
	v_add_u32_e32 v10, s0, v215
	s_nop 0
	v_cndmask_b32_e32 v80, v200, v80, vcc
	v_cmp_lt_u32_e32 vcc, s66, v10
	v_add_u32_e32 v10, s0, v216
	s_nop 0
	v_cndmask_b32_e32 v81, v200, v81, vcc
	v_cmp_lt_u32_e32 vcc, s66, v10
	v_add_u32_e32 v10, s0, v217
	s_nop 0
	v_cndmask_b32_e32 v82, v200, v82, vcc
	v_cmp_lt_u32_e32 vcc, s66, v10
	v_add_u32_e32 v10, s0, v218
	s_nop 0
	v_cndmask_b32_e32 v83, v200, v83, vcc
	v_cmp_lt_u32_e32 vcc, s66, v10
	v_add_u32_e32 v10, s0, v219
	s_nop 0
	v_cndmask_b32_e32 v84, v200, v84, vcc
	v_cmp_lt_u32_e32 vcc, s66, v10
	v_add_u32_e32 v10, s0, v220
	s_nop 0
	v_cndmask_b32_e32 v85, v200, v85, vcc
	v_cmp_lt_u32_e32 vcc, s66, v10
	v_add_u32_e32 v10, s0, v221
	s_nop 0
	v_cndmask_b32_e32 v86, v200, v86, vcc
	v_cmp_lt_u32_e32 vcc, s66, v10
	v_add_u32_e32 v10, s0, v222
	s_nop 0
	v_cndmask_b32_e32 v87, v200, v87, vcc
	v_cmp_lt_u32_e32 vcc, s66, v10
	v_add_u32_e32 v10, s0, v223
	s_nop 0
	v_cndmask_b32_e32 v88, v200, v88, vcc
	v_cmp_lt_u32_e32 vcc, s66, v10
	v_add_u32_e32 v10, s0, v224
	s_nop 0
	v_cndmask_b32_e32 v89, v200, v89, vcc
	v_cmp_lt_u32_e32 vcc, s66, v10
	v_add_u32_e32 v10, s0, v225
	s_nop 0
	v_cndmask_b32_e32 v90, v200, v90, vcc
	v_cmp_lt_u32_e32 vcc, s66, v10
	v_add_u32_e32 v10, s0, v226
	s_nop 0
	v_cndmask_b32_e32 v91, v200, v91, vcc
	v_cmp_lt_u32_e32 vcc, s66, v10
	v_add_u32_e32 v10, s0, v227
	s_nop 0
	v_cndmask_b32_e32 v92, v200, v92, vcc
	v_cmp_lt_u32_e32 vcc, s66, v10
	v_add_u32_e32 v10, s0, v228
	s_nop 0
	v_cndmask_b32_e32 v93, v200, v93, vcc
	v_cmp_lt_u32_e32 vcc, s66, v10
	v_add_u32_e32 v10, s0, v229
	s_nop 0
	v_cndmask_b32_e32 v94, v200, v94, vcc
	v_cmp_lt_u32_e32 vcc, s66, v10
	s_nop 1
	v_cndmask_b32_e32 v95, v200, v95, vcc
.LBB0_365:
	v_add_f32_e32 v11, 0, v235
	v_add_f32_e32 v11, v236, v11
	v_add_f32_e32 v11, v237, v11
	v_add_f32_e32 v11, v238, v11
	v_add_f32_e32 v11, v239, v11
	v_add_f32_e32 v11, v240, v11
	v_add_f32_e32 v11, v241, v11
	v_add_f32_e32 v11, v242, v11
	v_add_f32_e32 v11, v243, v11
	v_add_f32_e32 v11, v244, v11
	v_add_f32_e32 v11, v245, v11
	v_sub_f32_e32 v10, v233, v234
	v_add_f32_e32 v11, v246, v11
	v_add_f32_e32 v11, v247, v11
	v_exp_f32_e32 v10, v10
	v_add_f32_e32 v11, v248, v11
	v_add_f32_e32 v11, v249, v11
	v_add_f32_e32 v160, v250, v11
	v_fmac_f32_e32 v160, v232, v10
	s_mov_b64 vcc, s[98:99]
	s_cbranch_vccz .Lrs_4
	v_mul_f32_e32 v78, v10, v78
	v_mul_f32_e32 v79, v10, v79
	v_mul_f32_e32 v76, v10, v76
	v_mul_f32_e32 v77, v10, v77
	v_mul_f32_e32 v74, v10, v74
	v_mul_f32_e32 v75, v10, v75
	v_mul_f32_e32 v72, v10, v72
	v_mul_f32_e32 v73, v10, v73
	v_mul_f32_e32 v70, v10, v70
	v_mul_f32_e32 v71, v10, v71
	v_mul_f32_e32 v68, v10, v68
	v_mul_f32_e32 v69, v10, v69
	v_mul_f32_e32 v66, v10, v66
	v_mul_f32_e32 v67, v10, v67
	v_mul_f32_e32 v64, v10, v64
	v_mul_f32_e32 v65, v10, v65
	v_mul_f32_e32 v62, v10, v62
	v_mul_f32_e32 v63, v10, v63
	v_mul_f32_e32 v60, v10, v60
	v_mul_f32_e32 v61, v10, v61
	v_mul_f32_e32 v58, v10, v58
	v_mul_f32_e32 v59, v10, v59
	v_mul_f32_e32 v56, v10, v56
	v_mul_f32_e32 v57, v10, v57
	v_mul_f32_e32 v54, v10, v54
	v_mul_f32_e32 v55, v10, v55
	v_mul_f32_e32 v52, v10, v52
	v_mul_f32_e32 v53, v10, v53
	v_mul_f32_e32 v50, v10, v50
	v_mul_f32_e32 v51, v10, v51
	v_mul_f32_e32 v48, v10, v48
	v_mul_f32_e32 v49, v10, v49
.Lrs_4:
	v_max3_f32 v10, v80, s18, v81
	v_max3_f32 v10, v10, v82, v83
	v_max3_f32 v10, v10, v84, v85
	v_max3_f32 v10, v10, v86, v87
	v_max3_f32 v10, v10, v88, v89
	v_max3_f32 v10, v10, v90, v91
	v_max3_f32 v10, v10, v92, v93
	v_max3_f32 v10, v10, v94, v95
	ds_bpermute_b32 v11, v209, v10
	v_mov_b32_e32 v232, v160
	s_waitcnt lgkmcnt(0)
	v_max3_f32 v161, v14, v10, v11
	v_sub_f32_e32 v255, v161, v14
	v_cmp_lt_f32_e64 s[98:99], 4.0, v255
	s_nop 1
	v_cndmask_b32_e64 v161, v14, v161, s[98:99]
	v_sub_f32_e32 v11, v80, v161
	v_exp_f32_e32 v11, v11
	v_sub_f32_e32 v13, v81, v161
	v_sub_f32_e32 v10, v14, v161
	v_exp_f32_e32 v13, v13
	v_sub_f32_e32 v14, v82, v161
	v_exp_f32_e32 v14, v14
	v_sub_f32_e32 v80, v83, v161
	v_exp_f32_e32 v81, v80
	v_sub_f32_e32 v80, v84, v161
	v_add_f32_e32 v12, 0, v11
	v_exp_f32_e32 v82, v80
	v_sub_f32_e32 v80, v85, v161
	v_add_f32_e32 v12, v13, v12
	v_exp_f32_e32 v83, v80
	v_sub_f32_e32 v80, v86, v161
	v_add_f32_e32 v12, v14, v12
	v_exp_f32_e32 v85, v80
	v_sub_f32_e32 v80, v87, v161
	v_add_f32_e32 v12, v81, v12
	v_exp_f32_e32 v86, v80
	v_sub_f32_e32 v80, v88, v161
	v_add_f32_e32 v12, v82, v12
	v_exp_f32_e32 v87, v80
	v_sub_f32_e32 v80, v89, v161
	v_add_f32_e32 v12, v83, v12
	v_exp_f32_e32 v88, v80
	v_sub_f32_e32 v80, v90, v161
	v_add_f32_e32 v12, v85, v12
	v_exp_f32_e32 v89, v80
	v_sub_f32_e32 v80, v91, v161
	v_add_f32_e32 v12, v86, v12
	v_exp_f32_e32 v90, v80
	v_sub_f32_e32 v80, v92, v161
	v_add_f32_e32 v12, v87, v12
	v_exp_f32_e32 v91, v80
	v_sub_f32_e32 v80, v93, v161
	v_add_f32_e32 v12, v88, v12
	v_exp_f32_e32 v92, v80
	v_sub_f32_e32 v80, v94, v161
	v_add_f32_e32 v12, v89, v12
	v_exp_f32_e32 v93, v80
	v_sub_f32_e32 v80, v95, v161
	v_add_f32_e32 v12, v90, v12
	v_exp_f32_e32 v94, v80
	v_add_f32_e32 v12, v91, v12
	v_exp_f32_e32 v10, v10
	v_add_f32_e32 v12, v92, v12
	v_add_f32_e32 v12, v93, v12
	v_add_f32_e32 v84, v94, v12
	v_fmac_f32_e32 v84, v0, v10
	s_mov_b64 vcc, s[98:99]
	s_cbranch_vccz .Lrs_5
	v_mul_f32_e32 v46, v10, v46
	v_mul_f32_e32 v47, v10, v47
	v_mul_f32_e32 v44, v10, v44
	v_mul_f32_e32 v45, v10, v45
	v_mul_f32_e32 v42, v10, v42
	v_mul_f32_e32 v43, v10, v43
	v_mul_f32_e32 v40, v10, v40
	v_mul_f32_e32 v41, v10, v41
	v_mul_f32_e32 v38, v10, v38
	v_mul_f32_e32 v39, v10, v39
	v_mul_f32_e32 v36, v10, v36
	v_mul_f32_e32 v37, v10, v37
	v_mul_f32_e32 v34, v10, v34
	v_mul_f32_e32 v35, v10, v35
	v_mul_f32_e32 v32, v10, v32
	v_mul_f32_e32 v33, v10, v33
	v_mul_f32_e32 v30, v10, v30
	v_mul_f32_e32 v31, v10, v31
	v_mul_f32_e32 v28, v10, v28
	v_mul_f32_e32 v29, v10, v29
	v_mul_f32_e32 v26, v10, v26
	v_mul_f32_e32 v27, v10, v27
	v_mul_f32_e32 v24, v10, v24
	v_mul_f32_e32 v25, v10, v25
	v_mul_f32_e32 v22, v10, v22
	v_mul_f32_e32 v23, v10, v23
	v_mul_f32_e32 v20, v10, v20
	v_mul_f32_e32 v21, v10, v21
	v_mul_f32_e32 v18, v10, v18
	v_mul_f32_e32 v19, v10, v19
	v_mul_f32_e32 v16, v10, v16
	v_mul_f32_e32 v17, v10, v17
.Lrs_5:
	v_cvt_pk_bf16_f32 v80, v11, v13
	v_cvt_pk_bf16_f32 v82, v82, v83
	v_cvt_pk_bf16_f32 v83, v85, v86
	v_cvt_pk_bf16_f32 v10, v87, v88
	v_cvt_pk_bf16_f32 v11, v89, v90
	v_cvt_pk_bf16_f32 v12, v91, v92
	v_cvt_pk_bf16_f32 v13, v93, v94
	ds_read2_b64 v[86:89], v231 offset0:64 offset1:66
	ds_read2_b64 v[90:93], v231 offset0:68 offset1:70
	v_cvt_pk_bf16_f32 v81, v14, v81
	s_waitcnt lgkmcnt(1)
	v_mfma_f32_32x32x16_bf16 v[64:79], v[86:89], v[6:9], v[64:79]
	v_mov_b32_e32 v14, v161
	v_mov_b32_e32 v0, v84
	v_mfma_f32_32x32x16_bf16 v[32:47], v[86:89], v[80:83], v[32:47]
	ds_read2_b64 v[86:89], v15 offset0:128 offset1:130
	s_waitcnt lgkmcnt(0)
	v_mfma_f32_32x32x16_bf16 v[48:63], v[86:89], v[6:9], v[48:63]
	ds_read2_b64 v[6:9], v15 offset0:132 offset1:134
	s_waitcnt lgkmcnt(0)
	s_barrier
	v_mfma_f32_32x32x16_bf16 v[16:31], v[86:89], v[80:83], v[16:31]
	v_mfma_f32_32x32x16_bf16 v[64:79], v[90:93], v[2:5], v[64:79]
	v_mfma_f32_32x32x16_bf16 v[32:47], v[90:93], v[10:13], v[32:47]
	v_mfma_f32_32x32x16_bf16 v[48:63], v[6:9], v[2:5], v[48:63]
	v_mfma_f32_32x32x16_bf16 v[16:31], v[6:9], v[10:13], v[16:31]
	s_add_i32 s0, s64, -5
	s_cmp_ge_i32 s0, s56
	s_cbranch_scc1 .LBB0_332

.LBB0_378:
	s_nop 10
	v_max3_f32 v2, v80, s18, v81
	v_max3_f32 v2, v2, v82, v83
	v_max3_f32 v2, v2, v84, v85
	v_max3_f32 v2, v2, v86, v87
	v_max3_f32 v2, v2, v88, v89
	v_max3_f32 v2, v2, v90, v91
	v_max3_f32 v2, v2, v92, v93
	v_max3_f32 v2, v2, v94, v95
	ds_bpermute_b32 v3, v209, v2
	s_and_b64 vcc, exec, s[38:39]
	s_waitcnt lgkmcnt(0)
	v_max3_f32 v231, v234, v2, v3
	v_sub_f32_e32 v255, v231, v234
	v_cmp_lt_f32_e64 s[98:99], 4.0, v255
	s_nop 1
	v_cndmask_b32_e64 v231, v234, v231, s[98:99]
	v_sub_f32_e32 v2, v80, v231
	v_exp_f32_e32 v15, v2
	v_sub_f32_e32 v2, v81, v231
	v_exp_f32_e32 v233, v2
	v_sub_f32_e32 v2, v82, v231
	v_exp_f32_e32 v235, v2
	v_sub_f32_e32 v2, v83, v231
	v_exp_f32_e32 v236, v2
	v_sub_f32_e32 v2, v84, v231
	v_exp_f32_e32 v237, v2
	v_sub_f32_e32 v2, v85, v231
	v_exp_f32_e32 v238, v2
	v_sub_f32_e32 v2, v86, v231
	v_exp_f32_e32 v239, v2
	v_sub_f32_e32 v2, v87, v231
	v_exp_f32_e32 v240, v2
	v_sub_f32_e32 v2, v88, v231
	v_exp_f32_e32 v241, v2
	v_sub_f32_e32 v2, v89, v231
	v_exp_f32_e32 v242, v2
	v_sub_f32_e32 v2, v90, v231
	v_exp_f32_e32 v243, v2
	v_sub_f32_e32 v2, v91, v231
	v_exp_f32_e32 v244, v2
	v_sub_f32_e32 v2, v92, v231
	v_exp_f32_e32 v245, v2
	v_sub_f32_e32 v2, v93, v231
	v_exp_f32_e32 v246, v2
	v_sub_f32_e32 v2, v94, v231
	v_exp_f32_e32 v247, v2
	v_sub_f32_e32 v2, v95, v231
	v_mfma_f32_32x32x16_bf16 v[80:95], v[168:171], v[112:115], 0
	v_exp_f32_e32 v248, v2
	v_cvt_pk_bf16_f32 v6, v15, v233
	v_cvt_pk_bf16_f32 v7, v235, v236
	v_cvt_pk_bf16_f32 v8, v237, v238
	v_cvt_pk_bf16_f32 v9, v239, v240
	v_cvt_pk_bf16_f32 v2, v241, v242
	v_cvt_pk_bf16_f32 v3, v243, v244
	v_mfma_f32_32x32x16_bf16 v[80:95], v[164:167], v[116:119], v[80:95]
	v_cvt_pk_bf16_f32 v4, v245, v246
	v_cvt_pk_bf16_f32 v5, v247, v248
	v_mfma_f32_32x32x16_bf16 v[80:95], v[10:13], v[120:123], v[80:95]
	v_mfma_f32_32x32x16_bf16 v[80:95], v[160:163], v[124:127], v[80:95]
	s_cbranch_vccnz .LBB0_381
	s_cmp_lt_i32 s3, s62
	s_cselect_b64 s[0:1], -1, 0
	s_cmp_gt_i32 s3, s55
	s_cselect_b64 s[26:27], -1, 0
	s_or_b64 s[0:1], s[0:1], s[26:27]
	s_andn2_b64 vcc, exec, s[0:1]
	s_cbranch_vccnz .LBB0_381
	s_sub_i32 s0, s2, s63
	v_add_u32_e32 v10, s0, v214
	v_cmp_lt_u32_e32 vcc, s66, v10
	v_add_u32_e32 v10, s0, v215
	s_nop 0
	v_cndmask_b32_e32 v80, v200, v80, vcc
	v_cmp_lt_u32_e32 vcc, s66, v10
	v_add_u32_e32 v10, s0, v216
	s_nop 0
	v_cndmask_b32_e32 v81, v200, v81, vcc
	v_cmp_lt_u32_e32 vcc, s66, v10
	v_add_u32_e32 v10, s0, v217
	s_nop 0
	v_cndmask_b32_e32 v82, v200, v82, vcc
	v_cmp_lt_u32_e32 vcc, s66, v10
	v_add_u32_e32 v10, s0, v218
	s_nop 0
	v_cndmask_b32_e32 v83, v200, v83, vcc
	v_cmp_lt_u32_e32 vcc, s66, v10
	v_add_u32_e32 v10, s0, v219
	s_nop 0
	v_cndmask_b32_e32 v84, v200, v84, vcc
	v_cmp_lt_u32_e32 vcc, s66, v10
	v_add_u32_e32 v10, s0, v220
	s_nop 0
	v_cndmask_b32_e32 v85, v200, v85, vcc
	v_cmp_lt_u32_e32 vcc, s66, v10
	v_add_u32_e32 v10, s0, v221
	s_nop 0
	v_cndmask_b32_e32 v86, v200, v86, vcc
	v_cmp_lt_u32_e32 vcc, s66, v10
	v_add_u32_e32 v10, s0, v222
	s_nop 0
	v_cndmask_b32_e32 v87, v200, v87, vcc
	v_cmp_lt_u32_e32 vcc, s66, v10
	v_add_u32_e32 v10, s0, v223
	s_nop 0
	v_cndmask_b32_e32 v88, v200, v88, vcc
	v_cmp_lt_u32_e32 vcc, s66, v10
	v_add_u32_e32 v10, s0, v224
	s_nop 0
	v_cndmask_b32_e32 v89, v200, v89, vcc
	v_cmp_lt_u32_e32 vcc, s66, v10
	v_add_u32_e32 v10, s0, v225
	s_nop 0
	v_cndmask_b32_e32 v90, v200, v90, vcc
	v_cmp_lt_u32_e32 vcc, s66, v10
	v_add_u32_e32 v10, s0, v226
	s_nop 0
	v_cndmask_b32_e32 v91, v200, v91, vcc
	v_cmp_lt_u32_e32 vcc, s66, v10
	v_add_u32_e32 v10, s0, v227
	s_nop 0
	v_cndmask_b32_e32 v92, v200, v92, vcc
	v_cmp_lt_u32_e32 vcc, s66, v10
	v_add_u32_e32 v10, s0, v228
	s_nop 0
	v_cndmask_b32_e32 v93, v200, v93, vcc
	v_cmp_lt_u32_e32 vcc, s66, v10
	v_add_u32_e32 v10, s0, v229
	s_nop 0
	v_cndmask_b32_e32 v94, v200, v94, vcc
	v_cmp_lt_u32_e32 vcc, s66, v10
	s_nop 1
	v_cndmask_b32_e32 v95, v200, v95, vcc
.LBB0_381:
	v_add_f32_e32 v11, 0, v15
	v_add_f32_e32 v11, v233, v11
	v_add_f32_e32 v11, v235, v11
	v_add_f32_e32 v11, v236, v11
	v_add_f32_e32 v11, v237, v11
	v_add_f32_e32 v11, v238, v11
	v_add_f32_e32 v11, v239, v11
	v_add_f32_e32 v11, v240, v11
	v_add_f32_e32 v11, v241, v11
	v_add_f32_e32 v11, v242, v11
	v_add_f32_e32 v11, v243, v11
	v_sub_f32_e32 v10, v234, v231
	v_add_f32_e32 v11, v244, v11
	v_add_f32_e32 v11, v245, v11
	v_exp_f32_e32 v10, v10
	v_add_f32_e32 v11, v246, v11
	v_add_f32_e32 v11, v247, v11
	v_add_f32_e32 v233, v248, v11
	v_fmac_f32_e32 v233, v232, v10
	s_mov_b64 vcc, s[98:99]
	s_cbranch_vccz .Lrs_6
	v_mul_f32_e32 v78, v10, v78
	v_mul_f32_e32 v79, v10, v79
	v_mul_f32_e32 v76, v10, v76
	v_mul_f32_e32 v77, v10, v77
	v_mul_f32_e32 v74, v10, v74
	v_mul_f32_e32 v75, v10, v75
	v_mul_f32_e32 v72, v10, v72
	v_mul_f32_e32 v73, v10, v73
	v_mul_f32_e32 v70, v10, v70
	v_mul_f32_e32 v71, v10, v71
	v_mul_f32_e32 v68, v10, v68
	v_mul_f32_e32 v69, v10, v69
	v_mul_f32_e32 v66, v10, v66
	v_mul_f32_e32 v67, v10, v67
	v_mul_f32_e32 v64, v10, v64
	v_mul_f32_e32 v65, v10, v65
	v_mul_f32_e32 v62, v10, v62
	v_mul_f32_e32 v63, v10, v63
	v_mul_f32_e32 v60, v10, v60
	v_mul_f32_e32 v61, v10, v61
	v_mul_f32_e32 v58, v10, v58
	v_mul_f32_e32 v59, v10, v59
	v_mul_f32_e32 v56, v10, v56
	v_mul_f32_e32 v57, v10, v57
	v_mul_f32_e32 v54, v10, v54
	v_mul_f32_e32 v55, v10, v55
	v_mul_f32_e32 v52, v10, v52
	v_mul_f32_e32 v53, v10, v53
	v_mul_f32_e32 v50, v10, v50
	v_mul_f32_e32 v51, v10, v51
	v_mul_f32_e32 v48, v10, v48
	v_mul_f32_e32 v49, v10, v49
.Lrs_6:
	v_max3_f32 v10, v80, s18, v81
	v_max3_f32 v10, v10, v82, v83
	v_max3_f32 v10, v10, v84, v85
	v_max3_f32 v10, v10, v86, v87
	v_max3_f32 v10, v10, v88, v89
	v_max3_f32 v10, v10, v90, v91
	v_max3_f32 v10, v10, v92, v93
	v_max3_f32 v10, v10, v94, v95
	ds_bpermute_b32 v11, v209, v10
	s_waitcnt lgkmcnt(0)
	v_max3_f32 v235, v14, v10, v11
	v_sub_f32_e32 v255, v235, v14
	v_cmp_lt_f32_e64 s[98:99], 4.0, v255
	s_nop 1
	v_cndmask_b32_e64 v235, v14, v235, s[98:99]
	v_sub_f32_e32 v11, v80, v235
	v_exp_f32_e32 v11, v11
	v_sub_f32_e32 v13, v81, v235
	v_sub_f32_e32 v10, v14, v235
	v_exp_f32_e32 v13, v13
	v_sub_f32_e32 v14, v82, v235
	v_exp_f32_e32 v14, v14
	v_sub_f32_e32 v15, v83, v235
	v_exp_f32_e32 v81, v15
	v_sub_f32_e32 v15, v84, v235
	v_add_f32_e32 v12, 0, v11
	v_exp_f32_e32 v82, v15
	v_sub_f32_e32 v15, v85, v235
	v_add_f32_e32 v12, v13, v12
	v_exp_f32_e32 v83, v15
	v_sub_f32_e32 v15, v86, v235
	v_add_f32_e32 v12, v14, v12
	v_exp_f32_e32 v84, v15
	v_sub_f32_e32 v15, v87, v235
	v_add_f32_e32 v12, v81, v12
	v_exp_f32_e32 v85, v15
	v_sub_f32_e32 v15, v88, v235
	v_add_f32_e32 v12, v82, v12
	v_exp_f32_e32 v86, v15
	v_sub_f32_e32 v15, v89, v235
	v_add_f32_e32 v12, v83, v12
	v_exp_f32_e32 v87, v15
	v_sub_f32_e32 v15, v90, v235
	v_add_f32_e32 v12, v84, v12
	v_exp_f32_e32 v88, v15
	v_sub_f32_e32 v15, v91, v235
	v_add_f32_e32 v12, v85, v12
	v_exp_f32_e32 v89, v15
	v_sub_f32_e32 v15, v92, v235
	v_add_f32_e32 v12, v86, v12
	v_exp_f32_e32 v90, v15
	v_sub_f32_e32 v15, v93, v235
	v_add_f32_e32 v12, v87, v12
	v_exp_f32_e32 v91, v15
	v_sub_f32_e32 v15, v94, v235
	v_add_f32_e32 v12, v88, v12
	v_exp_f32_e32 v92, v15
	v_sub_f32_e32 v15, v95, v235
	v_add_f32_e32 v12, v89, v12
	v_exp_f32_e32 v93, v15
	v_add_f32_e32 v12, v90, v12
	v_exp_f32_e32 v10, v10
	v_add_f32_e32 v12, v91, v12
	v_add_f32_e32 v12, v92, v12
	v_add_f32_e32 v15, v93, v12
	v_fmac_f32_e32 v15, v0, v10
	v_add_u32_e32 v0, 0x3800, v230
	s_mov_b64 vcc, s[98:99]
	s_cbranch_vccz .Lrs_7
	v_mul_f32_e32 v46, v10, v46
	v_mul_f32_e32 v47, v10, v47
	v_mul_f32_e32 v44, v10, v44
	v_mul_f32_e32 v45, v10, v45
	v_mul_f32_e32 v42, v10, v42
	v_mul_f32_e32 v43, v10, v43
	v_mul_f32_e32 v40, v10, v40
	v_mul_f32_e32 v41, v10, v41
	v_mul_f32_e32 v38, v10, v38
	v_mul_f32_e32 v39, v10, v39
	v_mul_f32_e32 v36, v10, v36
	v_mul_f32_e32 v37, v10, v37
	v_mul_f32_e32 v34, v10, v34
	v_mul_f32_e32 v35, v10, v35
	v_mul_f32_e32 v32, v10, v32
	v_mul_f32_e32 v33, v10, v33
	v_mul_f32_e32 v30, v10, v30
	v_mul_f32_e32 v31, v10, v31
	v_mul_f32_e32 v28, v10, v28
	v_mul_f32_e32 v29, v10, v29
	v_mul_f32_e32 v26, v10, v26
	v_mul_f32_e32 v27, v10, v27
	v_mul_f32_e32 v24, v10, v24
	v_mul_f32_e32 v25, v10, v25
	v_mul_f32_e32 v22, v10, v22
	v_mul_f32_e32 v23, v10, v23
	v_mul_f32_e32 v20, v10, v20
	v_mul_f32_e32 v21, v10, v21
	v_mul_f32_e32 v18, v10, v18
	v_mul_f32_e32 v19, v10, v19
	v_mul_f32_e32 v16, v10, v16
	v_mul_f32_e32 v17, v10, v17
.Lrs_7:
	v_cvt_pk_bf16_f32 v80, v11, v13
	v_cvt_pk_bf16_f32 v82, v82, v83
	v_cvt_pk_bf16_f32 v83, v84, v85
	v_cvt_pk_bf16_f32 v10, v86, v87
	v_cvt_pk_bf16_f32 v11, v88, v89
	v_cvt_pk_bf16_f32 v12, v90, v91
	ds_read2_b64 v[84:87], v0 offset1:2
	ds_read2_b64 v[88:91], v0 offset0:4 offset1:6
	v_add_u32_e32 v0, 0x4000, v230
	v_cvt_pk_bf16_f32 v81, v14, v81
	s_waitcnt lgkmcnt(1)
	v_mfma_f32_32x32x16_bf16 v[64:79], v[84:87], v[6:9], v[64:79]
	v_cvt_pk_bf16_f32 v13, v92, v93
	v_mfma_f32_32x32x16_bf16 v[32:47], v[84:87], v[80:83], v[32:47]
	ds_read2_b64 v[84:87], v0 offset0:64 offset1:66
	s_waitcnt lgkmcnt(0)
	v_mfma_f32_32x32x16_bf16 v[48:63], v[84:87], v[6:9], v[48:63]
	ds_read2_b64 v[6:9], v0 offset0:68 offset1:70
	s_waitcnt lgkmcnt(0)
	s_barrier
	v_mfma_f32_32x32x16_bf16 v[16:31], v[84:87], v[80:83], v[16:31]
	v_mfma_f32_32x32x16_bf16 v[64:79], v[88:91], v[2:5], v[64:79]
	v_mfma_f32_32x32x16_bf16 v[32:47], v[88:91], v[10:13], v[32:47]
	v_mfma_f32_32x32x16_bf16 v[48:63], v[6:9], v[2:5], v[48:63]
	v_mfma_f32_32x32x16_bf16 v[16:31], v[6:9], v[10:13], v[16:31]
